# GLA output phase: loop-invariant RMSNorm gain loads hoisted out of the item loop (loaded once per phase), per-item reload and its drain removed
# baseline (speedup 1.0000x reference)
; #define LAS __attribute__((address_space(3)))
; __device__ __forceinline__ void gla_c_item(const Args& a, int l, int item, LAS unsigned char* L, int tid, int wave, int lane, bool smp = false) {
;     ...
;         const int s = tid >> 3, dg = tid & 7;
;         u32x4 ko, qo;
; #pragma unroll
;         for (int i = 0; i < 4; ++i) { const int d = 8 * dg + 2 * i; const float b0 = Bm[s * 64 + d], b1 = Bm[s * 64 + d + 1];
;             ko[i] = cvtpk(bflo(kr[i]) * __expf(-b0), bfhi(kr[i]) * __expf(-b1)); qo[i] = cvtpk(bflo(qr[i]) * __expf(b0), bfhi(qr[i]) * __expf(b1)); }
;         *(LAS u32x4*)(KI + s * 72 + 8 * dg) = ko; *(LAS u32x4*)(QD + s * 72 + 8 * dg) = qo;
; #pragma unroll
;         for (int j = 0; j < 4; ++j) { const unsigned w0 = j < 2 ? sg0[2 * j] : sg1[2 * j - 4], w1 = j < 2 ? sg0[2 * j + 1] : sg1[2 * j - 3];
;             ST[(16 * dg + 4 * j) * 72 + (s ^ (8 * dg))] = (bf16_t)(w0 & 0xffffu); ST[(16 * dg + 4 * j + 1) * 72 + (s ^ (8 * dg))] = (bf16_t)(w0 >> 16);
;             ST[(16 * dg + 4 * j + 2) * 72 + (s ^ (8 * dg))] = (bf16_t)(w1 & 0xffffu); ST[(16 * dg + 4 * j + 3) * 72 + (s ^ (8 * dg))] = (bf16_t)(w1 >> 16); }
;     }
;     gla_vt(pv0, pv1, L, tid);
;     lds_barrier();
;     {
;         const int r32 = lane & 31, hi = lane >> 5, ti = wave >> 2, vi = wave & 3;
;         bf16x8 qf[4];
; #pragma unroll
;         for (int kd = 0; kd < 4; ++kd) qf[kd] = *(const LAS bf16x8*)(QD + (32 * ti + r32) * 72 + 16 * kd + 8 * hi);
;         f32x16 o;
; #pragma unroll
;         for (int i = 0; i < 16; ++i) o[i] = 0.f;
; #pragma unroll
;         for (int kd = 0; kd < 4; ++kd) { const int srow = 32 * vi + r32; o = MFMA32(qf[kd], *(const LAS bf16x8*)(ST + srow * 72 + ((16 * kd + 8 * hi) ^ (8 * ((srow >> 4) & 7)))), o); }
;         const int tcol = 32 * ti + r32;
; #pragma unroll
;         for (int sb = 0; sb < 2; ++sb) {
;             if (sb <= ti) {
;                 f32x16 sc;
; #pragma unroll
;                 for (int i = 0; i < 16; ++i) sc[i] = 0.f;
; #pragma unroll
;                 for (int kd = 0; kd < 4; ++kd) sc = MFMA32(*(const LAS bf16x8*)(KI + (32 * sb + r32) * 72 + 16 * kd + 8 * hi), qf[kd], sc);
; #pragma unroll
;                 for (int r = 0; r < 16; ++r) { const int srow = 32 * sb + crow(r, hi); if (srow > tcol) sc[r] = 0.f; }
; #pragma unroll
;                 for (int kq = 0; kq < 2; ++kq) {
.LBB0_1068:
	s_or_b64 exec, exec, s[4:5]
	v_mov_b32_e32 v0, v200
	s_mov_b64 s[52:53], s[80:81]
	s_waitcnt lgkmcnt(0)
	s_barrier
	s_and_b64 vcc, exec, s[78:79]
	v_readfirstlane_b32 s4, v0
	s_cbranch_vccnz .LBB0_1075
	v_ashrrev_i32_e32 v68, 3, v0
	v_and_b32_e32 v5, 7, v0
	v_lshlrev_b32_e32 v10, 8, v68
	v_lshlrev_b32_e32 v11, 5, v5
	s_movk_i32 s5, 0x90
	v_lshlrev_b32_e32 v4, 3, v5
	v_lshlrev_b32_e32 v6, 4, v5
	v_add3_u32 v69, 0, v10, v11
	v_mul_lo_u32 v10, v68, s5
	v_add3_u32 v70, 0, v10, v6
	v_xor_b32_e32 v10, v4, v68
	v_mul_u32_u24_e32 v12, 0x900, v5
	v_lshlrev_b32_e32 v10, 1, v10
	v_readlane_b32 s7, v246, 56
	v_add3_u32 v72, 0, v12, v10
	s_ashr_i32 s6, s4, 8
	v_add3_u32 v71, s7, v12, v10
	v_bfe_u32 v12, v0, 5, 1
	v_and_b32_e32 v10, 31, v0
	s_lshl_b32 s18, s6, 5
	v_lshlrev_b32_e32 v15, 4, v12
	v_lshlrev_b32_e32 v18, 3, v12
	v_lshlrev_b32_e32 v12, 2, v12
	v_or_b32_e32 v13, s18, v10
	v_or_b32_e32 v22, 2, v12
	v_cmp_gt_i32_e64 s[10:11], v22, v13
	s_bfe_u32 s19, s4, 0x20006
	v_or_b32_e32 v22, 3, v12
	v_writelane_b32 v248, s10, 9
	v_lshl_or_b32 v16, s19, 5, v10
	v_mov_b32_e32 v17, s7
	v_writelane_b32 v248, s11, 10
	v_cmp_gt_i32_e64 s[10:11], v22, v13
	v_lshrrev_b32_e32 v19, 1, v16
	v_or_b32_e32 v22, 8, v12
	v_writelane_b32 v248, s10, 21
	v_mad_u32_u24 v17, v16, s5, v17
	v_bitop3_b32 v21, v19, v18, 56 bitop3:0x6c
	v_writelane_b32 v248, s11, 22
	v_cmp_gt_i32_e64 s[10:11], v22, v13
	v_lshl_add_u32 v73, v21, 1, v17
	v_or_b32_e32 v21, 16, v18
	v_writelane_b32 v248, s10, 23
	v_or_b32_e32 v23, 9, v12
	v_bitop3_b32 v21, v19, v21, 56 bitop3:0x6c
	v_writelane_b32 v248, s11, 24
	v_cmp_gt_i32_e64 s[10:11], v23, v13
	v_and_b32_e32 v20, 56, v19
	v_lshl_add_u32 v74, v21, 1, v17
	v_or_b32_e32 v21, 32, v18
	v_writelane_b32 v248, s10, 25
	v_or_b32_e32 v23, 10, v12
	v_or_b32_e32 v24, 17, v12
	v_bitop3_b32 v21, v19, v21, 56 bitop3:0x6c
	v_mad_u32_u24 v16, v16, s5, 0
	v_writelane_b32 v248, s11, 26
	v_cmp_gt_i32_e64 s[10:11], v23, v13
	v_or_b32_e32 v23, 11, v12
	v_cmp_gt_i32_e64 s[24:25], v24, v13
	v_or_b32_e32 v24, 18, v12
	v_lshlrev_b32_e32 v20, 1, v20
	v_lshl_add_u32 v75, v21, 1, v17
	v_or_b32_e32 v21, 48, v18
	s_cmp_gt_i32 s6, -1
	v_cmp_gt_i32_e64 s[20:21], v23, v13
	v_or_b32_e32 v23, 16, v12
	v_cmp_gt_i32_e64 s[26:27], v24, v13
	v_or_b32_e32 v24, 19, v12
	v_add3_u32 v77, v16, v18, v20
	v_bitop3_b32 v18, v19, v22, 56 bitop3:0x6c
	v_mul_lo_u32 v14, v13, s5
	s_cselect_b64 s[4:5], -1, 0
	v_cmp_gt_i32_e64 s[28:29], v24, v13
	v_or_b32_e32 v24, 24, v12
	v_lshl_add_u32 v78, v18, 1, v16
	v_bitop3_b32 v18, v19, v23, 56 bitop3:0x6c
	s_cmp_gt_i32 s6, 0
	v_or_b32_e32 v20, 33, v12
	v_lshlrev_b32_e32 v2, 3, v0
	v_lshlrev_b32_e32 v7, 5, v0
	v_writelane_b32 v248, s10, 27
	v_cmp_gt_i32_e64 s[30:31], v24, v13
	v_lshl_add_u32 v79, v18, 1, v16
	v_bitop3_b32 v18, v19, v24, 56 bitop3:0x6c
	s_cselect_b64 s[80:81], -1, 0
	v_and_or_b32 v0, v0, 63, 32
	v_cmp_gt_i32_e64 s[42:43], v20, v13
	v_or_b32_e32 v20, 34, v12
	v_or_b32_e32 v22, 41, v12
	v_or_b32_e32 v24, s18, v12
	s_lshl_b32 s18, s19, 7
	v_readlane_b32 s54, v246, 57
	v_bitop3_b32 v21, v19, v21, 56 bitop3:0x6c
	v_writelane_b32 v248, s11, 28
	v_lshl_add_u32 v80, v18, 1, v16
	v_mul_u32_u24_e32 v18, 0x90, v0
	v_or_b32_e32 v0, 32, v12
	v_cmp_gt_i32_e64 s[44:45], v20, v13
	v_or_b32_e32 v20, 35, v12
	v_cmp_gt_i32_e64 s[6:7], v22, v13
	v_or_b32_e32 v22, 42, v12
	s_add_i32 s18, s54, s18
	v_lshl_add_u32 v76, v21, 1, v17
	v_mul_u32_u24_e32 v21, 0x90, v10
	v_cmp_gt_i32_e64 s[40:41], v0, v13
	v_cmp_gt_i32_e64 s[46:47], v20, v13
	v_or_b32_e32 v20, 40, v12
	v_cmp_gt_i32_e64 s[10:11], v22, v13
	v_or_b32_e32 v22, 43, v12
	v_lshl_add_u32 v10, v10, 2, s18
	v_readlane_b32 s18, v248, 15
	v_bitop3_b32 v0, v19, v0, 56 bitop3:0x6c
	v_cmp_gt_i32_e64 s[12:13], v22, v13
	v_or_b32_e32 v22, 48, v12
	v_readlane_b32 s19, v248, 16
	s_lshl_b32 s82, s18, 7
	s_mov_b64 s[56:57], s[78:79]
	v_readlane_b32 s64, v249, 16
	v_lshl_add_u32 v81, v0, 1, v16
	v_bitop3_b32 v0, v19, v20, 56 bitop3:0x6c
	s_lshl_b64 s[18:19], s[82:83], 2
	v_readlane_b32 s70, v249, 22
	v_lshl_add_u32 v82, v0, 1, v16
	v_bitop3_b32 v0, v19, v22, 56 bitop3:0x6c
	v_lshlrev_b32_e32 v8, 7, v68
	v_readlane_b32 s71, v249, 23
	s_add_u32 s18, s70, s18
	v_lshl_add_u32 v83, v0, 1, v16
	v_bitop3_b32 v0, v19, v12, 56 bitop3:0x4e
	v_ashrrev_i32_e32 v9, 31, v8
	v_cmp_gt_i32_e64 s[22:23], v23, v13
	v_or_b32_e32 v23, 49, v12
	s_addc_u32 s19, s71, s19
	v_lshl_add_u32 v84, v0, 1, v16
	v_lshlrev_b32_e32 v0, 6, v5
	v_or_b32_e32 v25, 25, v12
	v_cmp_gt_i32_e64 s[16:17], v23, v13
	v_or_b32_e32 v23, 50, v12
	v_lshl_add_u64 v[58:59], s[18:19], 0, v[0:1]
	v_lshlrev_b64 v[8:9], 1, v[8:9]
	v_readlane_b32 s18, v246, 43
	v_cmp_gt_i32_e64 s[34:35], v25, v13
	v_or_b32_e32 v25, 26, v12
	v_cmp_gt_i32_e64 s[60:61], v23, v13
	v_or_b32_e32 v23, 51, v12
	v_or_b32_e32 v8, v8, v11
	v_readlane_b32 s19, v246, 44
	v_cmp_gt_i32_e64 s[36:37], v25, v13
	v_or_b32_e32 v25, 27, v12
	v_cmp_gt_i32_e64 s[62:63], v23, v13
	v_or_b32_e32 v23, 56, v12
	v_readlane_b32 s65, v249, 17
	v_readlane_b32 s74, v249, 26
	v_readlane_b32 s75, v249, 27
	v_readlane_b32 s76, v249, 28
	v_readlane_b32 s77, v249, 29
	s_movk_i32 s55, 0x210
	v_lshl_add_u64 v[60:61], s[18:19], 0, v[8:9]
	v_readlane_b32 s18, v246, 47
	v_ashrrev_i32_e32 v3, 31, v2
	v_add_u32_e32 v14, 0, v14
	v_add_u32_e32 v17, 0, v15
	v_cmp_gt_i32_e64 s[58:59], v12, v13
	v_cmp_lt_i32_e64 s[8:9], v12, v13
	v_cmp_gt_i32_e64 s[38:39], v25, v13
	v_readlane_b32 s66, v249, 18
	v_readlane_b32 s67, v249, 19
	v_readlane_b32 s68, v249, 20
	v_readlane_b32 s69, v249, 21
	v_readlane_b32 s72, v249, 24
	v_readlane_b32 s73, v249, 25
	v_readlane_b32 s78, v249, 30
	v_readlane_b32 s79, v249, 31
	v_readlane_b32 s76, v248, 19
	v_readlane_b32 s74, v248, 2
	v_cmp_gt_i32_e64 s[64:65], v23, v13
	v_or_b32_e32 v23, 57, v12
	v_or_b32_e32 v25, 58, v12
	v_or_b32_e32 v26, 59, v12
	v_mul_lo_u32 v12, v24, s55
	v_mul_lo_u32 v16, v68, s55
	v_readlane_b32 s19, v246, 48
	v_cmp_gt_i32_e64 s[48:49], v20, v13
	v_cmp_gt_i32_e64 s[14:15], v22, v13
	s_mov_b64 s[78:79], s[56:57]
	s_mov_b64 s[56:57], s[58:59]
	v_readlane_b32 s77, v248, 20
	v_readlane_b32 s75, v248, 3
	v_add3_u32 v85, s54, v16, v0
	v_lshl_add_u64 v[62:63], v[2:3], 2, s[18:19]
	v_lshlrev_b32_e32 v0, 1, v4
	v_lshlrev_b32_e32 v64, 1, v6
	v_add_u32_e32 v86, 0, v7
	v_add_u32_e32 v87, v14, v15
	v_add_u32_e32 v88, v17, v21
	v_add_u32_e32 v89, v17, v18
	v_add_u32_e32 v90, v10, v12
	v_readlane_b32 s59, v247, 17
	v_readlane_b32 s18, v248, 0
	v_cmp_gt_i32_e64 s[66:67], v23, v13
	v_cmp_gt_i32_e64 s[68:69], v25, v13
	v_cmp_gt_i32_e64 s[70:71], v26, v13
	s_mov_b64 s[72:73], 0
	v_readlane_b32 s19, v248, 1
	global_load_dwordx4 v[132:135], v[58:59], off offset:48
	global_load_dwordx4 v[136:139], v[58:59], off offset:32
	global_load_dwordx4 v[140:143], v[58:59], off offset:16
	global_load_dwordx4 v[144:147], v[58:59], off
	s_branch .LBB0_1071
; #define LAS __attribute__((address_space(3)))
; __device__ __forceinline__ int crow(int r, int hi) { return (r & 3) + 8 * (r >> 2) + 4 * hi; }
; __device__ __forceinline__ void lds_barrier() { asm volatile("s_waitcnt lgkmcnt(0)\n\ts_barrier" ::: "memory"); }
; __device__ __forceinline__ void gla_c_item(const Args& a, int l, int item, LAS unsigned char* L, int tid, int wave, int lane, bool smp = false) {
;     ...
;         for (int r = 0; r < 16; ++r) OL[(32 * ti + crow(r, hi)) * 132 + 32 * vi + r32] = o[r];
;     }
;     lds_barrier();
;     {
;         const int t = tid >> 3, sg = tid & 7;
;         float x[16]; float q = 0.f;
; #pragma unroll
;         for (int j = 0; j < 4; ++j) { const f32x4 v = *(const LAS f32x4*)(OL + t * 132 + 16 * sg + 4 * j); x[4 * j] = v[0]; x[4 * j + 1] = v[1]; x[4 * j + 2] = v[2]; x[4 * j + 3] = v[3]; q += (v[0] * v[0] + v[1] * v[1]) + (v[2] * v[2] + v[3] * v[3]); }
;         q += __shfl_xor(q, 1); q += __shfl_xor(q, 2); q += __shfl_xor(q, 4);
;         const float rs = rsqrtf(q * (1.0f / 128.0f) + EPS);
;         const float* ng = a.in[11] + l * 128 + 16 * sg;
;         float gt[16];
; #pragma unroll
;         for (int i = 0; i < 4; ++i) { gt[2 * i] = bflo(g0[i]); gt[2 * i + 1] = bfhi(g0[i]); gt[8 + 2 * i] = bflo(g1[i]); gt[8 + 2 * i + 1] = bfhi(g1[i]); }
;         float y[16];
; #pragma unroll
;         for (int i = 0; i < 16; ++i) { const float gv = gt[i]; const float sl = gv / (1.0f + __expf(-gv)); y[i] = x[i] * rs * ng[i] * sl; }
.LBB0_1070:
	s_nop 10
	ds_write2_b32 v90, v2, v3 offset1:132
	v_add_u32_e32 v2, 0x400, v90
	ds_write2_b32 v2, v4, v5 offset0:8 offset1:140
	v_add_u32_e32 v2, 0x1000, v90
	ds_write2_b32 v2, v6, v7 offset0:32 offset1:164
	v_add_u32_e32 v2, 0x1400, v90
	ds_write2_b32 v2, v8, v9 offset0:40 offset1:172
	v_add_u32_e32 v2, 0x2000, v90
	ds_write2_b32 v2, v10, v11 offset0:64 offset1:196
	v_add_u32_e32 v2, 0x2400, v90
	ds_write2_b32 v2, v12, v13 offset0:72 offset1:204
	v_add_u32_e32 v2, 0x3000, v90
	ds_write2_b32 v2, v14, v15 offset0:96 offset1:228
	v_add_u32_e32 v2, 0x3400, v90
	ds_write2_b32 v2, v16, v17 offset0:104 offset1:236
	s_waitcnt lgkmcnt(0)
	s_barrier
	ds_read_b128 v[24:27], v85
	ds_read_b128 v[18:21], v85 offset:16
	ds_read_b128 v[10:13], v85 offset:32
	ds_read_b128 v[2:5], v85 offset:48
	v_readlane_b32 s54, v246, 6
	s_waitcnt lgkmcnt(3)
	v_pk_mul_f32 v[6:7], v[26:27], v[26:27]
	v_pk_mul_f32 v[8:9], v[24:25], v[24:25]
	v_readlane_b32 s55, v246, 7
	v_pk_mov_b32 v[14:15], v[8:9], v[6:7] op_sel:[1,0]
	v_mov_b32_e32 v9, v7
	v_pk_add_f32 v[6:7], v[14:15], v[8:9]
	s_waitcnt lgkmcnt(2)
	v_pk_mul_f32 v[8:9], v[20:21], v[20:21]
	v_pk_mul_f32 v[14:15], v[18:19], v[18:19]
	v_pk_add_f32 v[6:7], v[6:7], v[6:7] op_sel:[0,1] op_sel_hi:[1,0]
	v_pk_mov_b32 v[16:17], v[14:15], v[8:9] op_sel:[1,0]
	v_mov_b32_e32 v15, v9
	v_pk_add_f32 v[8:9], v[16:17], v[14:15]
	s_waitcnt lgkmcnt(0)
	v_mul_f32_e32 v14, v2, v2
	v_mul_f32_e32 v15, v3, v3
	v_pk_add_f32 v[8:9], v[8:9], v[8:9] op_sel:[0,1] op_sel_hi:[1,0]
	v_mov_b32_e32 v7, v14
	v_mov_b32_e32 v9, v15
	v_pk_add_f32 v[6:7], v[6:7], v[8:9]
	v_mul_f32_e32 v8, v11, v11
	v_mul_f32_e32 v14, v13, v13
	v_mul_f32_e32 v16, v4, v4
	v_mul_f32_e32 v17, v5, v5
	v_pk_fma_f32 v[8:9], v[10:11], v[10:11], v[8:9] op_sel_hi:[1,1,0]
	v_pk_fma_f32 v[14:15], v[12:13], v[12:13], v[14:15] op_sel_hi:[1,1,0]
	v_mov_b32_e32 v9, v16
	v_mov_b32_e32 v15, v17
	v_pk_add_f32 v[8:9], v[8:9], v[14:15]
	s_lshl_b32 s82, s82, 1
	v_pk_add_f32 v[6:7], v[6:7], v[8:9]
	v_and_b32_e32 v8, 64, v205
	v_add_f32_e32 v6, v6, v7
	v_xor_b32_e32 v7, 1, v205
	v_add_u32_e32 v8, 64, v8
	v_cmp_lt_i32_e32 vcc, v7, v8
	v_and_b32_e32 v9, 0xffff0000, v38
	v_mov_b32_e32 v65, v1
	v_cndmask_b32_e32 v7, v205, v7, vcc
	v_lshlrev_b32_e32 v7, 2, v7
	ds_bpermute_b32 v7, v7, v6
	v_readlane_b32 s19, v246, 38
	s_add_i32 s18, s18, s52
	s_add_i32 s59, s59, s19
	s_waitcnt lgkmcnt(0)
	v_add_f32_e32 v6, v6, v7
	v_xor_b32_e32 v7, 2, v205
	v_cmp_lt_i32_e32 vcc, v7, v8
	s_nop 1
	v_cndmask_b32_e32 v7, v205, v7, vcc
	v_lshlrev_b32_e32 v7, 2, v7
	ds_bpermute_b32 v7, v7, v6
	s_waitcnt lgkmcnt(0)
	v_add_f32_e32 v6, v6, v7
	v_xor_b32_e32 v7, 4, v205
	v_cmp_lt_i32_e32 vcc, v7, v8
	v_lshlrev_b32_e32 v8, 16, v38
	s_nop 0
	v_cndmask_b32_e32 v7, v205, v7, vcc
	v_lshlrev_b32_e32 v7, 2, v7
	ds_bpermute_b32 v7, v7, v6
	s_waitcnt lgkmcnt(0)
	v_add_f32_e32 v6, v6, v7
	v_fmamk_f32 v6, v6, 0x3c000000, v201
	v_cmp_gt_f32_e32 vcc, s3, v6
	v_mul_f32_e32 v7, 0x4b800000, v6
	s_nop 0
	v_cndmask_b32_e32 v6, v6, v7, vcc
	v_rsq_f32_e32 v6, v6
	s_nop 0
	v_mul_f32_e32 v7, 0x45800000, v6
	v_cndmask_b32_e32 v32, v6, v7, vcc
	v_mul_f32_e32 v6, 0xbfb8aa3b, v8
	v_mul_f32_e32 v7, 0xbfb8aa3b, v9
	v_exp_f32_e32 v6, v6
	v_exp_f32_e32 v7, v7
	v_pk_mul_f32 v[44:45], v[24:25], v[32:33] op_sel_hi:[1,0]
	v_lshlrev_b32_e32 v33, 16, v39
	v_mul_f32_e32 v38, 0xbfb8aa3b, v33
	v_pk_add_f32 v[6:7], v[6:7], 1.0 op_sel_hi:[1,0]
	v_exp_f32_e32 v38, v38
	v_div_scale_f32 v14, vcc, v7, v7, v9
	v_rcp_f32_e32 v15, v14
	v_pk_mul_f32 v[26:27], v[26:27], v[32:33] op_sel_hi:[1,0]
	v_fma_f32 v16, -v14, v15, 1.0
	v_fmac_f32_e32 v15, v16, v15
	v_div_scale_f32 v16, vcc, v9, v7, v9
	v_mul_f32_e32 v17, v16, v15
	v_fma_f32 v22, -v14, v17, v16
	v_fmac_f32_e32 v17, v22, v15
	v_fma_f32 v14, -v14, v17, v16
	v_div_fmas_f32 v14, v14, v15, v17
	v_div_fixup_f32 v43, v14, v7, v9
	v_div_scale_f32 v7, vcc, v6, v6, v8
	v_rcp_f32_e32 v9, v7
	s_nop 0
	v_fma_f32 v14, -v7, v9, 1.0
	v_fmac_f32_e32 v9, v14, v9
	v_div_scale_f32 v14, vcc, v8, v6, v8
	v_mul_f32_e32 v15, v14, v9
	v_fma_f32 v16, -v7, v15, v14
	v_fmac_f32_e32 v15, v16, v9
	v_fma_f32 v7, -v7, v15, v14
	v_div_fmas_f32 v7, v7, v9, v15
	v_div_fixup_f32 v42, v7, v6, v8
	v_pk_mul_f32 v[28:29], v[144:145], v[44:45]
	s_nop 0
	v_pk_mul_f32 v[28:29], v[42:43], v[28:29]
	v_and_b32_e32 v42, 0xffff0000, v39
	v_mul_f32_e32 v39, 0xbfb8aa3b, v42
	v_exp_f32_e32 v39, v39
	v_pk_mul_f32 v[26:27], v[146:147], v[26:27]
	v_pk_add_f32 v[38:39], v[38:39], 1.0 op_sel_hi:[1,0]
	s_nop 0
	v_div_scale_f32 v43, vcc, v39, v39, v42
	v_rcp_f32_e32 v44, v43
	s_nop 0
	v_fma_f32 v45, -v43, v44, 1.0
	v_fmac_f32_e32 v44, v45, v44
	v_div_scale_f32 v45, vcc, v42, v39, v42
	v_mul_f32_e32 v46, v45, v44
	v_fma_f32 v47, -v43, v46, v45
	v_fmac_f32_e32 v46, v47, v44
	v_fma_f32 v43, -v43, v46, v45
	v_div_fmas_f32 v43, v43, v44, v46
	v_div_fixup_f32 v39, v43, v39, v42
	v_div_scale_f32 v42, vcc, v38, v38, v33
	v_rcp_f32_e32 v43, v42
	s_nop 0
	v_fma_f32 v44, -v42, v43, 1.0
	v_fmac_f32_e32 v43, v44, v43
	v_div_scale_f32 v44, vcc, v33, v38, v33
	v_mul_f32_e32 v45, v44, v43
	v_fma_f32 v46, -v42, v45, v44
	v_fmac_f32_e32 v45, v46, v43
	v_fma_f32 v42, -v42, v45, v44
	v_div_fmas_f32 v42, v42, v43, v45
	v_div_fixup_f32 v38, v42, v38, v33
	v_pk_mul_f32 v[26:27], v[38:39], v[26:27]
	v_lshlrev_b32_e32 v33, 16, v40
	v_and_b32_e32 v38, 0xffff0000, v40
	v_mul_f32_e32 v30, 0xbfb8aa3b, v33
	v_mul_f32_e32 v31, 0xbfb8aa3b, v38
	v_exp_f32_e32 v30, v30
	v_exp_f32_e32 v31, v31
	v_pk_mul_f32 v[18:19], v[18:19], v[32:33] op_sel_hi:[1,0]
	v_pk_add_f32 v[30:31], v[30:31], 1.0 op_sel_hi:[1,0]
	s_nop 0
	v_div_scale_f32 v39, vcc, v31, v31, v38
	v_rcp_f32_e32 v40, v39
; __device__ __forceinline__ unsigned cvtpk(float lo, float hi) { f32x2 v = {lo, hi}; bf16x2_t b = __builtin_convertvector(v, bf16x2_t); return __builtin_bit_cast(unsigned, b); }
; __device__ __forceinline__ void gla_c_item(const Args& a, int l, int item, LAS unsigned char* L, int tid, int wave, int lane, bool smp = false) {
;     ...
;         const float* ng = a.in[11] + l * 128 + 16 * sg;
;         float gt[16];
; #pragma unroll
;         for (int i = 0; i < 4; ++i) { gt[2 * i] = bflo(g0[i]); gt[2 * i + 1] = bfhi(g0[i]); gt[8 + 2 * i] = bflo(g1[i]); gt[8 + 2 * i + 1] = bfhi(g1[i]); }
;         float y[16];
; #pragma unroll
;         for (int i = 0; i < 16; ++i) { const float gv = gt[i]; const float sl = gv / (1.0f + __expf(-gv)); y[i] = x[i] * rs * ng[i] * sl; }
;         u32x4 w0, w1;
; #pragma unroll
;         for (int i = 0; i < 4; ++i) { w0[i] = cvtpk(y[2 * i], y[2 * i + 1]); w1[i] = cvtpk(y[8 + 2 * i], y[8 + 2 * i + 1]); }
;         bf16_t* mp = (bf16_t*)(a.ws + WS_MIX) + (size_t)(row0 + t) * D + h * 128 + 16 * sg;
;         *(u32x4*)mp = w0; *(u32x4*)(mp + 8) = w1;
	v_pk_mul_f32 v[18:19], v[140:141], v[18:19]
	v_fma_f32 v42, -v39, v40, 1.0
	v_fmac_f32_e32 v40, v42, v40
	v_div_scale_f32 v42, vcc, v38, v31, v38
	v_mul_f32_e32 v43, v42, v40
	v_fma_f32 v44, -v39, v43, v42
	v_fmac_f32_e32 v43, v44, v40
	v_fma_f32 v39, -v39, v43, v42
	v_div_fmas_f32 v39, v39, v40, v43
	v_div_fixup_f32 v31, v39, v31, v38
	v_div_scale_f32 v38, vcc, v30, v30, v33
	v_rcp_f32_e32 v39, v38
	s_nop 0
	v_fma_f32 v40, -v38, v39, 1.0
	v_fmac_f32_e32 v39, v40, v39
	v_div_scale_f32 v40, vcc, v33, v30, v33
	v_mul_f32_e32 v42, v40, v39
	v_fma_f32 v43, -v38, v42, v40
	v_fmac_f32_e32 v42, v43, v39
	v_fma_f32 v38, -v38, v42, v40
	v_div_fmas_f32 v38, v38, v39, v42
	v_div_fixup_f32 v30, v38, v30, v33
	v_pk_mul_f32 v[18:19], v[30:31], v[18:19]
	v_lshlrev_b32_e32 v30, 16, v41
	v_and_b32_e32 v31, 0xffff0000, v41
	v_mul_f32_e32 v22, 0xbfb8aa3b, v30
	v_mul_f32_e32 v23, 0xbfb8aa3b, v31
	v_exp_f32_e32 v22, v22
	v_exp_f32_e32 v23, v23
	s_nop 0
	v_pk_add_f32 v[22:23], v[22:23], 1.0 op_sel_hi:[1,0]
	s_nop 0
	v_div_scale_f32 v33, vcc, v23, v23, v31
	v_rcp_f32_e32 v38, v33
	s_nop 0
	v_fma_f32 v39, -v33, v38, 1.0
	v_fmac_f32_e32 v38, v39, v38
	v_div_scale_f32 v39, vcc, v31, v23, v31
	v_mul_f32_e32 v40, v39, v38
	v_fma_f32 v41, -v33, v40, v39
	v_fmac_f32_e32 v40, v41, v38
	v_fma_f32 v33, -v33, v40, v39
	v_div_fmas_f32 v33, v33, v38, v40
	v_div_fixup_f32 v23, v33, v23, v31
	v_div_scale_f32 v31, vcc, v22, v22, v30
	v_rcp_f32_e32 v33, v31
	s_nop 0
	v_fma_f32 v38, -v31, v33, 1.0
	v_fmac_f32_e32 v33, v38, v33
	v_div_scale_f32 v38, vcc, v30, v22, v30
	v_mul_f32_e32 v39, v38, v33
	v_fma_f32 v40, -v31, v39, v38
	v_fmac_f32_e32 v39, v40, v33
	v_fma_f32 v31, -v31, v39, v38
	v_div_fmas_f32 v31, v31, v33, v39
	v_pk_mul_f32 v[20:21], v[20:21], v[32:33] op_sel_hi:[1,0]
	v_div_fixup_f32 v22, v31, v22, v30
	v_pk_mul_f32 v[20:21], v[142:143], v[20:21]
	v_lshlrev_b32_e32 v24, 16, v34
	v_and_b32_e32 v25, 0xffff0000, v34
	v_pk_mul_f32 v[20:21], v[22:23], v[20:21]
	v_mul_f32_e32 v22, 0xbfb8aa3b, v24
	v_mul_f32_e32 v23, 0xbfb8aa3b, v25
	v_exp_f32_e32 v22, v22
	v_exp_f32_e32 v23, v23
	s_nop 0
	v_pk_add_f32 v[22:23], v[22:23], 1.0 op_sel_hi:[1,0]
	s_nop 0
	v_div_scale_f32 v30, vcc, v23, v23, v25
	v_rcp_f32_e32 v31, v30
	s_nop 0
	v_fma_f32 v33, -v30, v31, 1.0
	v_fmac_f32_e32 v31, v33, v31
	v_div_scale_f32 v33, vcc, v25, v23, v25
	v_mul_f32_e32 v34, v33, v31
	v_fma_f32 v38, -v30, v34, v33
	v_fmac_f32_e32 v34, v38, v31
	v_fma_f32 v30, -v30, v34, v33
	v_div_fmas_f32 v30, v30, v31, v34
	v_div_fixup_f32 v23, v30, v23, v25
	v_div_scale_f32 v25, vcc, v22, v22, v24
	v_rcp_f32_e32 v30, v25
	s_nop 0
	v_fma_f32 v31, -v25, v30, 1.0
	v_fmac_f32_e32 v30, v31, v30
	v_div_scale_f32 v31, vcc, v24, v22, v24
	v_mul_f32_e32 v33, v31, v30
	v_fma_f32 v34, -v25, v33, v31
	v_fmac_f32_e32 v33, v34, v30
	v_fma_f32 v25, -v25, v33, v31
	v_div_fmas_f32 v25, v25, v30, v33
	v_pk_mul_f32 v[10:11], v[10:11], v[32:33] op_sel_hi:[1,0]
	v_div_fixup_f32 v22, v25, v22, v24
	v_pk_mul_f32 v[10:11], v[136:137], v[10:11]
	s_nop 0
	v_pk_mul_f32 v[10:11], v[22:23], v[10:11]
	v_lshlrev_b32_e32 v22, 16, v35
	v_and_b32_e32 v23, 0xffff0000, v35
	v_mul_f32_e32 v14, 0xbfb8aa3b, v22
	v_mul_f32_e32 v15, 0xbfb8aa3b, v23
	v_exp_f32_e32 v14, v14
	v_exp_f32_e32 v15, v15
	s_nop 0
	v_pk_add_f32 v[14:15], v[14:15], 1.0 op_sel_hi:[1,0]
	s_nop 0
	v_div_scale_f32 v24, vcc, v15, v15, v23
	v_rcp_f32_e32 v25, v24
	s_nop 0
	v_fma_f32 v30, -v24, v25, 1.0
	v_fmac_f32_e32 v25, v30, v25
	v_div_scale_f32 v30, vcc, v23, v15, v23
	v_mul_f32_e32 v31, v30, v25
	v_fma_f32 v33, -v24, v31, v30
	v_fmac_f32_e32 v31, v33, v25
	v_fma_f32 v24, -v24, v31, v30
	v_div_fmas_f32 v24, v24, v25, v31
	v_div_fixup_f32 v15, v24, v15, v23
	v_div_scale_f32 v23, vcc, v14, v14, v22
	v_rcp_f32_e32 v24, v23
	v_pk_mul_f32 v[12:13], v[12:13], v[32:33] op_sel_hi:[1,0]
	v_pk_mul_f32 v[2:3], v[2:3], v[32:33] op_sel_hi:[1,0]
	v_pk_mul_f32 v[12:13], v[138:139], v[12:13]
	v_fma_f32 v25, -v23, v24, 1.0
	v_fmac_f32_e32 v24, v25, v24
	v_div_scale_f32 v25, vcc, v22, v14, v22
	v_mul_f32_e32 v30, v25, v24
	v_fma_f32 v31, -v23, v30, v25
	v_fmac_f32_e32 v30, v31, v24
	v_fma_f32 v23, -v23, v30, v25
	v_div_fmas_f32 v23, v23, v24, v30
	v_div_fixup_f32 v14, v23, v14, v22
	v_lshlrev_b32_e32 v16, 16, v36
	v_and_b32_e32 v17, 0xffff0000, v36
	v_pk_mul_f32 v[12:13], v[14:15], v[12:13]
	v_mul_f32_e32 v14, 0xbfb8aa3b, v16
	v_mul_f32_e32 v15, 0xbfb8aa3b, v17
	v_exp_f32_e32 v14, v14
	v_exp_f32_e32 v15, v15
	v_pk_mul_f32 v[2:3], v[2:3], v[132:133]
	v_lshlrev_b32_e32 v6, 16, v37
	v_and_b32_e32 v7, 0xffff0000, v37
	v_pk_add_f32 v[14:15], v[14:15], 1.0 op_sel_hi:[1,0]
	v_pk_mul_f32 v[4:5], v[4:5], v[32:33] op_sel_hi:[1,0]
	v_div_scale_f32 v22, vcc, v15, v15, v17
	v_rcp_f32_e32 v23, v22
	v_pk_mul_f32 v[4:5], v[4:5], v[134:135]
	v_fma_f32 v24, -v22, v23, 1.0
	v_fmac_f32_e32 v23, v24, v23
	v_div_scale_f32 v24, vcc, v17, v15, v17
	v_mul_f32_e32 v25, v24, v23
	v_fma_f32 v30, -v22, v25, v24
	v_fmac_f32_e32 v25, v30, v23
	v_fma_f32 v22, -v22, v25, v24
	v_div_fmas_f32 v22, v22, v23, v25
	v_div_fixup_f32 v15, v22, v15, v17
	v_div_scale_f32 v17, vcc, v14, v14, v16
	v_rcp_f32_e32 v22, v17
	s_nop 0
	v_fma_f32 v23, -v17, v22, 1.0
	v_fmac_f32_e32 v22, v23, v22
	v_div_scale_f32 v23, vcc, v16, v14, v16
	v_mul_f32_e32 v24, v23, v22
	v_fma_f32 v25, -v17, v24, v23
	v_fmac_f32_e32 v24, v25, v22
	v_fma_f32 v17, -v17, v24, v23
	v_div_fmas_f32 v17, v17, v22, v24
	v_div_fixup_f32 v14, v17, v14, v16
	v_pk_mul_f32 v[14:15], v[14:15], v[2:3]
	v_mul_f32_e32 v2, 0xbfb8aa3b, v6
	v_mul_f32_e32 v3, 0xbfb8aa3b, v7
	v_exp_f32_e32 v2, v2
	v_exp_f32_e32 v3, v3
	v_cvt_pk_bf16_f32 v8, v14, v15
	v_pk_add_f32 v[2:3], v[2:3], 1.0 op_sel_hi:[1,0]
	s_nop 0
	v_div_scale_f32 v16, vcc, v3, v3, v7
	v_rcp_f32_e32 v17, v16
	s_nop 0
	v_fma_f32 v22, -v16, v17, 1.0
	v_fmac_f32_e32 v17, v22, v17
	v_div_scale_f32 v22, vcc, v7, v3, v7
	v_mul_f32_e32 v23, v22, v17
	v_fma_f32 v24, -v16, v23, v22
	v_fmac_f32_e32 v23, v24, v17
	v_fma_f32 v16, -v16, v23, v22
	v_div_fmas_f32 v16, v16, v17, v23
	v_div_fixup_f32 v3, v16, v3, v7
	v_div_scale_f32 v7, vcc, v2, v2, v6
	v_rcp_f32_e32 v16, v7
	s_nop 0
	v_fma_f32 v17, -v7, v16, 1.0
	v_fmac_f32_e32 v16, v17, v16
	v_div_scale_f32 v17, vcc, v6, v2, v6
	v_mul_f32_e32 v22, v17, v16
	v_fma_f32 v23, -v7, v22, v17
	v_fmac_f32_e32 v22, v23, v16
	v_fma_f32 v7, -v7, v22, v17
	v_div_fmas_f32 v7, v7, v16, v22
	v_div_fixup_f32 v2, v7, v2, v6
	v_cvt_pk_bf16_f32 v6, v10, v11
	v_lshlrev_b64 v[10:11], 11, v[66:67]
	v_lshl_add_u64 v[10:11], s[54:55], 0, v[10:11]
	v_lshl_add_u64 v[10:11], v[10:11], 0, s[82:83]
	v_pk_mul_f32 v[16:17], v[2:3], v[4:5]
	v_cvt_pk_bf16_f32 v2, v28, v29
	v_cvt_pk_bf16_f32 v3, v26, v27
	v_cvt_pk_bf16_f32 v4, v18, v19
	v_cvt_pk_bf16_f32 v5, v20, v21
	v_lshl_add_u64 v[10:11], v[10:11], 0, v[64:65]
	v_cvt_pk_bf16_f32 v7, v12, v13
	v_cvt_pk_bf16_f32 v9, v16, v17
	s_cmpk_gt_i32 s18, 0x3ff
	s_cbranch_scc1 .Lgc_nopf
	global_load_dwordx4 v[124:127], v[112:113], off nt
	global_load_dwordx4 v[128:131], v[112:113], off offset:-16 nt
